# v165 with the F1 gathers dealt per wave: waves 0,1 in the prep, 2,3 after the alpha barrier, 4,5 after beta, 6,7 after gamma
# speedup vs baseline: 1.0261x; 1.0031x over previous
.LBB0_867:
	s_waitcnt vmcnt(4)
	s_add_i32 s91, s90, 1
	s_cmp_ge_i32 s91, s88
	s_cselect_b64 s[22:23], -1, 0
	s_cmp_lg_u32 s91, s99
	s_cselect_b32 s32, s98, 0
	s_andn2_b32 s32, s32, s22
	s_cmp_lg_u32 s32, 0
	s_cbranch_scc0 .Lf1_prep_slow
	s_cmp_ge_u32 s101, 2
	s_cbranch_scc1 .Lf1_prep_slow
	v_cvt_f32_f16 v28, v24
	v_lshrrev_b32_e32 v0, 16, v24
	v_cvt_f32_f16 v29, v0
	v_cvt_f32_f16 v30, v25
	v_lshrrev_b32_e32 v0, 16, v25
	v_cvt_f32_f16 v31, v0
	v_cvt_f32_f16 v32, v26
	v_lshrrev_b32_e32 v0, 16, v26
	v_cvt_f32_f16 v33, v0
	v_cvt_f32_f16 v34, v27
	v_lshrrev_b32_e32 v0, 16, v27
	v_cvt_f32_f16 v35, v0
	v_mul_f32_e32 v28, 0x3fb8aa3b, v28
	v_mul_f32_e32 v29, 0x3fb8aa3b, v29
	v_mul_f32_e32 v30, 0x3fb8aa3b, v30
	v_mul_f32_e32 v31, 0x3fb8aa3b, v31
	v_mul_f32_e32 v32, 0x3fb8aa3b, v32
	v_mul_f32_e32 v33, 0x3fb8aa3b, v33
	v_mul_f32_e32 v34, 0x3fb8aa3b, v34
	v_mul_f32_e32 v35, 0x3fb8aa3b, v35
	v_lshl_add_u64 v[230:231], v[230:231], 0, s[30:31]
	global_load_dwordx4 v[24:27], v[230:231], off
	ds_write_b128 v142, v[12:15] offset:36864
	v_lshl_add_u64 v[224:225], v[224:225], 0, s[30:31]
	global_load_dwordx4 v[12:15], v[224:225], off
	v_add_f32_dpp v28, v28, v28 row_shr:1 row_mask:0xf bank_mask:0xf bound_ctrl:1
	v_lshlrev_b32_e32 v68, 16, v16
	v_add_f32_dpp v29, v29, v29 row_shr:1 row_mask:0xf bank_mask:0xf bound_ctrl:1
	v_and_b32_e32 v69, 0xffff0000, v16
	v_add_f32_dpp v30, v30, v30 row_shr:1 row_mask:0xf bank_mask:0xf bound_ctrl:1
	v_lshlrev_b32_e32 v70, 16, v17
	v_add_f32_dpp v31, v31, v31 row_shr:1 row_mask:0xf bank_mask:0xf bound_ctrl:1
	v_and_b32_e32 v71, 0xffff0000, v17
	v_add_f32_dpp v32, v32, v32 row_shr:1 row_mask:0xf bank_mask:0xf bound_ctrl:1
	v_lshlrev_b32_e32 v72, 16, v18
	v_add_f32_dpp v33, v33, v33 row_shr:1 row_mask:0xf bank_mask:0xf bound_ctrl:1
	v_and_b32_e32 v73, 0xffff0000, v18
	v_add_f32_dpp v34, v34, v34 row_shr:1 row_mask:0xf bank_mask:0xf bound_ctrl:1
	v_lshlrev_b32_e32 v74, 16, v19
	v_add_f32_dpp v35, v35, v35 row_shr:1 row_mask:0xf bank_mask:0xf bound_ctrl:1
	v_and_b32_e32 v75, 0xffff0000, v19
	v_lshl_add_u64 v[226:227], v[226:227], 0, s[30:31]
	global_load_dwordx4 v[16:19], v[226:227], off
	v_add_f32_dpp v28, v28, v28 row_shr:2 row_mask:0xf bank_mask:0xf bound_ctrl:1
	v_lshlrev_b32_e32 v76, 16, v4
	v_add_f32_dpp v29, v29, v29 row_shr:2 row_mask:0xf bank_mask:0xf bound_ctrl:1
	v_and_b32_e32 v77, 0xffff0000, v4
	v_add_f32_dpp v30, v30, v30 row_shr:2 row_mask:0xf bank_mask:0xf bound_ctrl:1
	v_lshlrev_b32_e32 v78, 16, v5
	v_add_f32_dpp v31, v31, v31 row_shr:2 row_mask:0xf bank_mask:0xf bound_ctrl:1
	v_and_b32_e32 v79, 0xffff0000, v5
	v_add_f32_dpp v32, v32, v32 row_shr:2 row_mask:0xf bank_mask:0xf bound_ctrl:1
	v_lshlrev_b32_e32 v80, 16, v6
	v_add_f32_dpp v33, v33, v33 row_shr:2 row_mask:0xf bank_mask:0xf bound_ctrl:1
	v_and_b32_e32 v81, 0xffff0000, v6
	v_add_f32_dpp v34, v34, v34 row_shr:2 row_mask:0xf bank_mask:0xf bound_ctrl:1
	v_lshlrev_b32_e32 v82, 16, v7
	v_add_f32_dpp v35, v35, v35 row_shr:2 row_mask:0xf bank_mask:0xf bound_ctrl:1
	v_and_b32_e32 v83, 0xffff0000, v7
	v_lshl_add_u64 v[220:221], v[220:221], 0, s[30:31]
	global_load_dwordx4 v[4:7], v[220:221], off
	v_add_f32_dpp v28, v28, v28 row_shr:4 row_mask:0xf bank_mask:0xf bound_ctrl:1
	v_lshlrev_b32_e32 v84, 16, v20
	v_add_f32_dpp v29, v29, v29 row_shr:4 row_mask:0xf bank_mask:0xf bound_ctrl:1
	v_and_b32_e32 v85, 0xffff0000, v20
	v_add_f32_dpp v30, v30, v30 row_shr:4 row_mask:0xf bank_mask:0xf bound_ctrl:1
	v_lshlrev_b32_e32 v86, 16, v21
	v_add_f32_dpp v31, v31, v31 row_shr:4 row_mask:0xf bank_mask:0xf bound_ctrl:1
	v_and_b32_e32 v87, 0xffff0000, v21
	v_add_f32_dpp v32, v32, v32 row_shr:4 row_mask:0xf bank_mask:0xf bound_ctrl:1
	v_lshlrev_b32_e32 v88, 16, v22
	v_add_f32_dpp v33, v33, v33 row_shr:4 row_mask:0xf bank_mask:0xf bound_ctrl:1
	v_and_b32_e32 v89, 0xffff0000, v22
	v_add_f32_dpp v34, v34, v34 row_shr:4 row_mask:0xf bank_mask:0xf bound_ctrl:1
	v_lshlrev_b32_e32 v90, 16, v23
	v_add_f32_dpp v35, v35, v35 row_shr:4 row_mask:0xf bank_mask:0xf bound_ctrl:1
	v_and_b32_e32 v91, 0xffff0000, v23
	v_lshl_add_u64 v[228:229], v[228:229], 0, s[30:31]
	global_load_dwordx4 v[20:23], v[228:229], off
	v_add_f32_dpp v28, v28, v28 row_shr:8 row_mask:0xf bank_mask:0xf bound_ctrl:1
	v_lshlrev_b32_e32 v92, 16, v8
	v_add_f32_dpp v29, v29, v29 row_shr:8 row_mask:0xf bank_mask:0xf bound_ctrl:1
	v_and_b32_e32 v93, 0xffff0000, v8
	v_add_f32_dpp v30, v30, v30 row_shr:8 row_mask:0xf bank_mask:0xf bound_ctrl:1
	v_lshlrev_b32_e32 v94, 16, v9
	v_add_f32_dpp v31, v31, v31 row_shr:8 row_mask:0xf bank_mask:0xf bound_ctrl:1
	v_and_b32_e32 v95, 0xffff0000, v9
	v_add_f32_dpp v32, v32, v32 row_shr:8 row_mask:0xf bank_mask:0xf bound_ctrl:1
	v_lshlrev_b32_e32 v96, 16, v10
	v_add_f32_dpp v33, v33, v33 row_shr:8 row_mask:0xf bank_mask:0xf bound_ctrl:1
	v_and_b32_e32 v97, 0xffff0000, v10
	v_add_f32_dpp v34, v34, v34 row_shr:8 row_mask:0xf bank_mask:0xf bound_ctrl:1
	v_lshlrev_b32_e32 v98, 16, v11
	v_add_f32_dpp v35, v35, v35 row_shr:8 row_mask:0xf bank_mask:0xf bound_ctrl:1
	v_and_b32_e32 v99, 0xffff0000, v11
	v_lshl_add_u64 v[222:223], v[222:223], 0, s[30:31]
	global_load_dwordx4 v[8:11], v[222:223], off
	v_add_f32_dpp v28, v28, v28 row_bcast:15 row_mask:0xa bank_mask:0xf
	v_add_f32_dpp v29, v29, v29 row_bcast:15 row_mask:0xa bank_mask:0xf
	v_add_f32_dpp v30, v30, v30 row_bcast:15 row_mask:0xa bank_mask:0xf
	v_add_f32_dpp v31, v31, v31 row_bcast:15 row_mask:0xa bank_mask:0xf
	v_add_f32_dpp v32, v32, v32 row_bcast:15 row_mask:0xa bank_mask:0xf
	v_add_f32_dpp v33, v33, v33 row_bcast:15 row_mask:0xa bank_mask:0xf
	v_add_f32_dpp v34, v34, v34 row_bcast:15 row_mask:0xa bank_mask:0xf
	v_add_f32_dpp v35, v35, v35 row_bcast:15 row_mask:0xa bank_mask:0xf
	v_add_f32_dpp v28, v28, v28 row_bcast:31 row_mask:0xc bank_mask:0xf
	v_add_f32_dpp v29, v29, v29 row_bcast:31 row_mask:0xc bank_mask:0xf
	v_add_f32_dpp v30, v30, v30 row_bcast:31 row_mask:0xc bank_mask:0xf
	v_add_f32_dpp v31, v31, v31 row_bcast:31 row_mask:0xc bank_mask:0xf
	v_add_f32_dpp v32, v32, v32 row_bcast:31 row_mask:0xc bank_mask:0xf
	v_add_f32_dpp v33, v33, v33 row_bcast:31 row_mask:0xc bank_mask:0xf
	v_add_f32_dpp v34, v34, v34 row_bcast:31 row_mask:0xc bank_mask:0xf
	v_add_f32_dpp v35, v35, v35 row_bcast:31 row_mask:0xc bank_mask:0xf
	v_exp_f32_e32 v36, v28
	v_exp_f32_e32 v37, v29
	v_exp_f32_e32 v38, v30
	v_exp_f32_e32 v39, v31
	v_exp_f32_e32 v40, v32
	v_exp_f32_e32 v41, v33
	v_exp_f32_e32 v42, v34
	v_exp_f32_e32 v43, v35
	v_exp_f32_e64 v44, -v28
	v_exp_f32_e64 v45, -v29
	v_exp_f32_e64 v46, -v30
	v_exp_f32_e64 v47, -v31
	v_exp_f32_e64 v48, -v32
	v_exp_f32_e64 v49, -v33
	v_exp_f32_e64 v50, -v34
	v_exp_f32_e64 v51, -v35
	v_mov_b32_dpp v212, v36 wave_shr:1 row_mask:0xf bank_mask:0xf
	v_mov_b32_dpp v213, v37 wave_shr:1 row_mask:0xf bank_mask:0xf
	v_mov_b32_dpp v214, v38 wave_shr:1 row_mask:0xf bank_mask:0xf
	v_mov_b32_dpp v215, v39 wave_shr:1 row_mask:0xf bank_mask:0xf
	v_mov_b32_dpp v216, v40 wave_shr:1 row_mask:0xf bank_mask:0xf
	v_mov_b32_dpp v217, v41 wave_shr:1 row_mask:0xf bank_mask:0xf
	v_mov_b32_dpp v218, v42 wave_shr:1 row_mask:0xf bank_mask:0xf
	v_mov_b32_dpp v219, v43 wave_shr:1 row_mask:0xf bank_mask:0xf
	v_readlane_b32 s9, v254, 60
	s_add_i32 s9, s9, 0x21c00
	v_mov_b32_e32 v0, s9
	s_mov_b64 s[84:85], exec
	s_andn2_b64 exec, exec, s[38:39]
	ds_write_b128 v0, v[36:39]
	ds_write_b128 v0, v[40:43] offset:16
	s_mov_b64 exec, s[84:85]
	v_pk_mul_f32 v[68:69], v[212:213], v[68:69] neg_lo:[0,1] neg_hi:[0,1]
	v_pk_mul_f32 v[70:71], v[214:215], v[70:71] neg_lo:[0,1] neg_hi:[0,1]
	v_pk_mul_f32 v[72:73], v[216:217], v[72:73] neg_lo:[0,1] neg_hi:[0,1]
	v_pk_mul_f32 v[74:75], v[218:219], v[74:75] neg_lo:[0,1] neg_hi:[0,1]
	v_pk_mul_f32 v[76:77], v[36:37], v[76:77]
	v_pk_mul_f32 v[78:79], v[38:39], v[78:79]
	v_pk_mul_f32 v[80:81], v[40:41], v[80:81]
	v_pk_mul_f32 v[82:83], v[42:43], v[82:83]
	v_pk_mul_f32 v[84:85], v[44:45], v[84:85]
	v_pk_mul_f32 v[86:87], v[46:47], v[86:87]
	v_pk_mul_f32 v[88:89], v[48:49], v[88:89]
	v_pk_mul_f32 v[90:91], v[50:51], v[90:91]
	v_pk_mul_f32 v[92:93], v[44:45], v[92:93]
	v_pk_mul_f32 v[94:95], v[46:47], v[94:95]
	v_pk_mul_f32 v[96:97], v[48:49], v[96:97]
	v_pk_mul_f32 v[98:99], v[50:51], v[98:99]
	v_cvt_pk_bf16_f32 v52, v68, v69
	v_cvt_pk_bf16_f32 v53, v70, v71
	v_cvt_pk_bf16_f32 v54, v72, v73
	v_cvt_pk_bf16_f32 v55, v74, v75
	v_cvt_pk_bf16_f32 v56, v76, v77
	v_cvt_pk_bf16_f32 v57, v78, v79
	v_cvt_pk_bf16_f32 v58, v80, v81
	v_cvt_pk_bf16_f32 v59, v82, v83
	ds_write_b128 v142, v[52:55]
	ds_write_b128 v142, v[56:59] offset:27648
	v_cvt_pk_bf16_f32 v60, v84, v85
	v_cvt_pk_bf16_f32 v61, v86, v87
	v_cvt_pk_bf16_f32 v62, v88, v89
	v_cvt_pk_bf16_f32 v63, v90, v91
	v_cvt_pk_bf16_f32 v64, v92, v93
	v_cvt_pk_bf16_f32 v65, v94, v95
	v_cvt_pk_bf16_f32 v66, v96, v97
	v_cvt_pk_bf16_f32 v67, v98, v99
	ds_write_b128 v142, v[60:63] offset:9216
	ds_write_b128 v142, v[64:67] offset:18432
	s_branch .LBB0_877

.LBB0_894:
	s_waitcnt lgkmcnt(0)
	s_barrier
	s_cmp_lg_u32 s32, 0
	s_cbranch_scc0 .Lf1_dm2
	s_bitcmp1_b32 0xc, s101
	s_cbranch_scc0 .Lf1_dm2
	v_lshl_add_u64 v[230:231], v[230:231], 0, s[30:31]
	global_load_dwordx4 v[24:27], v[230:231], off
	v_lshl_add_u64 v[224:225], v[224:225], 0, s[30:31]
	global_load_dwordx4 v[12:15], v[224:225], off
	v_lshl_add_u64 v[226:227], v[226:227], 0, s[30:31]
	global_load_dwordx4 v[16:19], v[226:227], off
	v_lshl_add_u64 v[220:221], v[220:221], 0, s[30:31]
	global_load_dwordx4 v[4:7], v[220:221], off
	v_lshl_add_u64 v[228:229], v[228:229], 0, s[30:31]
	global_load_dwordx4 v[20:23], v[228:229], off
	v_lshl_add_u64 v[222:223], v[222:223], 0, s[30:31]
	global_load_dwordx4 v[8:11], v[222:223], off

.LBB0_896:
	s_waitcnt lgkmcnt(0)
	s_barrier
	s_cmp_lg_u32 s32, 0
	s_cbranch_scc0 .Lf1_dm3
	s_bitcmp1_b32 0x30, s101
	s_cbranch_scc0 .Lf1_dm3
	v_lshl_add_u64 v[230:231], v[230:231], 0, s[30:31]
	global_load_dwordx4 v[24:27], v[230:231], off
	v_lshl_add_u64 v[224:225], v[224:225], 0, s[30:31]
	global_load_dwordx4 v[12:15], v[224:225], off
	v_lshl_add_u64 v[226:227], v[226:227], 0, s[30:31]
	global_load_dwordx4 v[16:19], v[226:227], off
	v_lshl_add_u64 v[220:221], v[220:221], 0, s[30:31]
	global_load_dwordx4 v[4:7], v[220:221], off
	v_lshl_add_u64 v[228:229], v[228:229], 0, s[30:31]
	global_load_dwordx4 v[20:23], v[228:229], off
	v_lshl_add_u64 v[222:223], v[222:223], 0, s[30:31]
	global_load_dwordx4 v[8:11], v[222:223], off
.Lf1_dm3:
	s_andn2_b64 s[84:85], exec, s[12:13]
	s_andn2_b64 vcc, exec, s[12:13]
	s_cbranch_vccnz .LBB0_898
	ds_read_b64_tr_b16 v[46:47], v163 offset:65088
	ds_read_b64_tr_b16 v[44:45], v163 offset:64512
	ds_read_b128 v[48:51], v151
	s_waitcnt lgkmcnt(0)
	v_mfma_f32_16x16x32_bf16 v[44:47], v[44:47], v[48:51], 0
	s_nop 7
	v_cvt_pk_bf16_f32 v0, v44, v45
	v_cvt_pk_bf16_f32 v1, v46, v47
	ds_write_b64 v164, v[0:1] offset:46080
.LBB0_898:
	s_waitcnt lgkmcnt(0)
	s_barrier
	s_cmp_lg_u32 s32, 0
	s_cbranch_scc0 .Lf1_dm4
	s_bitcmp1_b32 0xc0, s101
	s_cbranch_scc0 .Lf1_dm4
	v_lshl_add_u64 v[230:231], v[230:231], 0, s[30:31]
	global_load_dwordx4 v[24:27], v[230:231], off
	v_lshl_add_u64 v[224:225], v[224:225], 0, s[30:31]
	global_load_dwordx4 v[12:15], v[224:225], off
	v_lshl_add_u64 v[226:227], v[226:227], 0, s[30:31]
	global_load_dwordx4 v[16:19], v[226:227], off
	v_lshl_add_u64 v[220:221], v[220:221], 0, s[30:31]
	global_load_dwordx4 v[4:7], v[220:221], off
	v_lshl_add_u64 v[228:229], v[228:229], 0, s[30:31]
	global_load_dwordx4 v[20:23], v[228:229], off
	v_lshl_add_u64 v[222:223], v[222:223], 0, s[30:31]
	global_load_dwordx4 v[8:11], v[222:223], off
.Lf1_dm4:
	s_and_b64 vcc, exec, s[84:85]
	s_cbranch_vccnz .LBB0_900
	ds_read_b64_tr_b16 v[44:45], v163 offset:50688
	ds_read_b64_tr_b16 v[46:47], v163 offset:51264
	ds_read_b128 v[48:51], v190 offset:64576
	s_waitcnt lgkmcnt(0)
	v_mfma_f32_16x16x32_bf16 v[44:47], v[44:47], v[48:51], 0
	s_nop 7
	v_cvt_pk_bf16_f32 v0, v44, v45
	v_cvt_pk_bf16_f32 v1, v46, v47
	ds_write_b64 v164, v[0:1] offset:64512
